# fix_phase loop hand-rewritten and unrolled 3x: 42 loads in flight per thread, masked stores
# baseline (speedup 1.0000x reference)
; __device__ __forceinline__ int otid(int wv) { int t; asm volatile("v_mbcnt_lo_u32_b32 %0, -1, 0\n\tv_mbcnt_hi_u32_b32 %0, -1, %0\n\tv_lshl_add_u32 %0, %1, 6, %0" : "=&v"(t) : "s"(wv)); return t; }
; __device__ void fix_phase(int wv, const Params& p, int li) {
;     const float* edge = (const float*)(p.ws + WS_EDGE); const float* cw = (const float*)(p.ws + WS_CW) + (size_t)li * 4 * NUP; bf16_t* act = (bf16_t*)(p.ws + WS_ACT);
;     const int total = 1024 * (FFD / 4);
;     const int tid = otid(wv);
;     for (int idx = blockIdx.x * NTHR + tid; idx < total; idx += gridDim.x * NTHR) {
;         const int e = idx / (FFD / 4), c = (idx % (FFD / 4)) * 4; const int band = e >> 1, hi = e & 1; const int R = band * 64 + (hi ? 63 : 0);
;         const int ca = (c >> 7) * 256 + (c & 127), cg_ = ca + 128;
;         const bool seqstart = (R == 0 || R == 8192 || R == 16384), seqend = (R == 8191 || R == 16383 || R == 32767);
;         const float* ep = edge + (size_t)band * 4 * NUP;
.LBB0_559:
	s_or_b64 exec, exec, s[0:1]
	v_readlane_b32 s0, v253, 0
	s_waitcnt lgkmcnt(0)
	s_barrier
	v_mbcnt_lo_u32_b32 v1, -1, 0
	v_mbcnt_hi_u32_b32 v1, -1, v1
	v_lshl_add_u32 v1, s33, 6, v1
	s_nop 0
	v_add_u32_e32 v36, s0, v1
	s_mov_b32 s0, 0xb0000
	v_cmp_gt_i32_e32 vcc, s0, v36
	s_and_saveexec_b64 s[4:5], vcc
	s_cbranch_execz .LBB0_592
	v_mov_b32_e32 v240, v36
.Lfix_loop:
	v_mov_b32_e32 v18, v240
	v_min_u32_e32 v8, 0xaffff, v18
	v_lshrrev_b32_e32 v6, 6, v8
	v_mov_b32_e32 v7, 0xba2e8ba3
	v_mul_hi_u32 v2, v6, v7
	v_lshrrev_b32_e32 v2, 3, v2
	v_mul_u32_u24_e32 v6, 0x2c0, v2
	v_sub_u32_e32 v3, v8, v6
	v_lshrrev_b32_e32 v4, 1, v2
	v_and_b32_e32 v5, 1, v2
	v_lshrrev_b32_e32 v6, 5, v3
	v_and_b32_e32 v7, 31, v3
	v_lshlrev_b32_e32 v7, 2, v7
	v_lshl_add_u32 v6, v6, 8, v7
	v_lshlrev_b32_e32 v15, 2, v6
	v_cmp_eq_u32_e64 s[8:9], 1, v5
	v_cmp_eq_u32_e64 s[10:11], 0, v4
	s_movk_i32 s36, 0x80
	v_cmp_eq_u32_e64 s[12:13], s36, v4
	s_movk_i32 s36, 0x100
	v_cmp_eq_u32_e64 s[14:15], s36, v4
	s_or_b64 s[10:11], s[10:11], s[12:13]
	s_or_b64 s[10:11], s[10:11], s[14:15]
	v_cndmask_b32_e64 v7, 1, 0, s[10:11]
	v_or_b32_e32 v7, v7, v5
	s_movk_i32 s36, 0x7f
	v_cmp_eq_u32_e64 s[10:11], s36, v4
	s_movk_i32 s36, 0xff
	v_cmp_eq_u32_e64 s[12:13], s36, v4
	s_movk_i32 s36, 0x1ff
	v_cmp_eq_u32_e64 s[14:15], s36, v4
	s_or_b64 s[10:11], s[10:11], s[12:13]
	s_or_b64 s[10:11], s[10:11], s[14:15]
	v_cndmask_b32_e64 v8, 1, 0, s[10:11]
	v_xor_b32_e32 v6, 1, v5
	v_or_b32_e32 v8, v8, v6
	v_cvt_f32_u32_e32 v16, v7
	v_cvt_f32_u32_e32 v17, v8
	v_sub_u32_e32 v6, 0, v7
	v_cndmask_b32_e64 v9, v6, 2, s[8:9]
	v_mul_u32_u24_e32 v10, 3, v5
	v_add_u32_e32 v6, 3, v8
	v_cndmask_b32_e64 v11, 1, v6, s[8:9]
	v_lshlrev_b32_e32 v6, 2, v4
	v_add_u32_e32 v7, v6, v9
	v_mul_u32_u24_e32 v7, 0x5800, v7
	v_add_u32_e32 v12, v7, v15
	v_add_u32_e32 v7, v6, v10
	v_mul_u32_u24_e32 v7, 0x5800, v7
	v_add_u32_e32 v13, v7, v15
	v_add_u32_e32 v7, v6, v11
	v_mul_u32_u24_e32 v7, 0x5800, v7
	v_add_u32_e32 v14, v7, v15
	global_load_dwordx4 v[20:23], v12, s[40:41]
	global_load_dwordx4 v[24:27], v12, s[40:41] offset:512
	global_load_dwordx4 v[28:31], v13, s[40:41]
	global_load_dwordx4 v[32:35], v13, s[40:41] offset:512
	global_load_dwordx4 v[40:43], v14, s[40:41]
	global_load_dwordx4 v[44:47], v14, s[40:41] offset:512
	global_load_dwordx4 v[48:51], v15, s[92:93]
	global_load_dwordx4 v[52:55], v15, s[92:93] offset:512
	global_load_dwordx4 v[56:59], v15, s[96:97]
	global_load_dwordx4 v[60:63], v15, s[96:97] offset:512
	global_load_dwordx4 v[64:67], v15, s[20:21]
	global_load_dwordx4 v[68:71], v15, s[20:21] offset:512
	global_load_dwordx4 v[72:75], v15, s[84:85]
	global_load_dwordx4 v[76:79], v15, s[84:85] offset:512
	v_mul_u32_u24_e32 v6, 63, v5
	v_lshl_add_u32 v6, v4, 6, v6
	v_mul_u32_u24_e32 v19, 0x1600, v6
	v_lshl_add_u32 v19, v3, 3, v19
	s_mul_i32 s36, s44, 1
	v_add_u32_e32 v98, s36, v240
	v_min_u32_e32 v88, 0xaffff, v98
	v_lshrrev_b32_e32 v86, 6, v88
	v_mov_b32_e32 v87, 0xba2e8ba3
	v_mul_hi_u32 v82, v86, v87
	v_lshrrev_b32_e32 v82, 3, v82
	v_mul_u32_u24_e32 v86, 0x2c0, v82
	v_sub_u32_e32 v83, v88, v86
	v_lshrrev_b32_e32 v84, 1, v82
	v_and_b32_e32 v85, 1, v82
	v_lshrrev_b32_e32 v86, 5, v83
	v_and_b32_e32 v87, 31, v83
	v_lshlrev_b32_e32 v87, 2, v87
	v_lshl_add_u32 v86, v86, 8, v87
	v_lshlrev_b32_e32 v95, 2, v86
	v_cmp_eq_u32_e64 s[8:9], 1, v85
	v_cmp_eq_u32_e64 s[10:11], 0, v84
	s_movk_i32 s36, 0x80
	v_cmp_eq_u32_e64 s[12:13], s36, v84
	s_movk_i32 s36, 0x100
	v_cmp_eq_u32_e64 s[14:15], s36, v84
	s_or_b64 s[10:11], s[10:11], s[12:13]
	s_or_b64 s[10:11], s[10:11], s[14:15]
	v_cndmask_b32_e64 v87, 1, 0, s[10:11]
	v_or_b32_e32 v87, v87, v85
	s_movk_i32 s36, 0x7f
	v_cmp_eq_u32_e64 s[10:11], s36, v84
	s_movk_i32 s36, 0xff
	v_cmp_eq_u32_e64 s[12:13], s36, v84
	s_movk_i32 s36, 0x1ff
	v_cmp_eq_u32_e64 s[14:15], s36, v84
	s_or_b64 s[10:11], s[10:11], s[12:13]
	s_or_b64 s[10:11], s[10:11], s[14:15]
	v_cndmask_b32_e64 v88, 1, 0, s[10:11]
	v_xor_b32_e32 v86, 1, v85
	v_or_b32_e32 v88, v88, v86
	v_cvt_f32_u32_e32 v96, v87
	v_cvt_f32_u32_e32 v97, v88
	v_sub_u32_e32 v86, 0, v87
	v_cndmask_b32_e64 v89, v86, 2, s[8:9]
	v_mul_u32_u24_e32 v90, 3, v85
	v_add_u32_e32 v86, 3, v88
	v_cndmask_b32_e64 v91, 1, v86, s[8:9]
	v_lshlrev_b32_e32 v86, 2, v84
	v_add_u32_e32 v87, v86, v89
	v_mul_u32_u24_e32 v87, 0x5800, v87
	v_add_u32_e32 v92, v87, v95
	v_add_u32_e32 v87, v86, v90
	v_mul_u32_u24_e32 v87, 0x5800, v87
	v_add_u32_e32 v93, v87, v95
	v_add_u32_e32 v87, v86, v91
	v_mul_u32_u24_e32 v87, 0x5800, v87
	v_add_u32_e32 v94, v87, v95
	global_load_dwordx4 v[100:103], v92, s[40:41]
	global_load_dwordx4 v[104:107], v92, s[40:41] offset:512
	global_load_dwordx4 v[108:111], v93, s[40:41]
	global_load_dwordx4 v[112:115], v93, s[40:41] offset:512
	global_load_dwordx4 v[120:123], v94, s[40:41]
	global_load_dwordx4 v[124:127], v94, s[40:41] offset:512
	global_load_dwordx4 v[128:131], v95, s[92:93]
	global_load_dwordx4 v[132:135], v95, s[92:93] offset:512
	global_load_dwordx4 v[136:139], v95, s[96:97]
	global_load_dwordx4 v[140:143], v95, s[96:97] offset:512
	global_load_dwordx4 v[144:147], v95, s[20:21]
	global_load_dwordx4 v[148:151], v95, s[20:21] offset:512
	global_load_dwordx4 v[152:155], v95, s[84:85]
	global_load_dwordx4 v[156:159], v95, s[84:85] offset:512
	v_mul_u32_u24_e32 v86, 63, v85
	v_lshl_add_u32 v86, v84, 6, v86
	v_mul_u32_u24_e32 v99, 0x1600, v86
	v_lshl_add_u32 v99, v83, 3, v99
	s_mul_i32 s36, s44, 2
	v_add_u32_e32 v178, s36, v240
	v_min_u32_e32 v168, 0xaffff, v178
	v_lshrrev_b32_e32 v166, 6, v168
	v_mov_b32_e32 v167, 0xba2e8ba3
	v_mul_hi_u32 v162, v166, v167
	v_lshrrev_b32_e32 v162, 3, v162
	v_mul_u32_u24_e32 v166, 0x2c0, v162
; __device__ __forceinline__ unsigned cvt_pk_bf16(float lo, float hi) { const f2_t v = {lo, hi}; const bf2_t b = __builtin_convertvector(v, bf2_t); return __builtin_bit_cast(unsigned, b); }
; __device__ void fix_phase(int wv, const Params& p, int li) {
;     ...
;     for (int idx = blockIdx.x * NTHR + tid; idx < total; idx += gridDim.x * NTHR) {
;         const int e = idx / (FFD / 4), c = (idx % (FFD / 4)) * 4; const int band = e >> 1, hi = e & 1; const int R = band * 64 + (hi ? 63 : 0);
;         const int ca = (c >> 7) * 256 + (c & 127), cg_ = ca + 128;
;         const bool seqstart = (R == 0 || R == 8192 || R == 16384), seqend = (R == 8191 || R == 16383 || R == 32767);
;         const float* ep = edge + (size_t)band * 4 * NUP;
;         f32x4 pa, pg, ua, ug, na, ng; const f32x4 zero = {0, 0, 0, 0};
;         if (!hi) { pa = seqstart ? zero : *(const f32x4*)(ep - NUP + ca); pg = seqstart ? zero : *(const f32x4*)(ep - NUP + cg_);
;             ua = *(const f32x4*)(ep + ca); ug = *(const f32x4*)(ep + cg_); na = *(const f32x4*)(ep + NUP + ca); ng = *(const f32x4*)(ep + NUP + cg_); }
;         else { pa = *(const f32x4*)(ep + 2 * NUP + ca); pg = *(const f32x4*)(ep + 2 * NUP + cg_); ua = *(const f32x4*)(ep + 3 * NUP + ca); ug = *(const f32x4*)(ep + 3 * NUP + cg_);
;             na = seqend ? zero : *(const f32x4*)(ep + 4 * NUP + ca); ng = seqend ? zero : *(const f32x4*)(ep + 4 * NUP + cg_); }
;         const f32x4 a = *(const f32x4*)(cw + ca) * pa + *(const f32x4*)(cw + NUP + ca) * ua + *(const f32x4*)(cw + 2 * NUP + ca) * na + *(const f32x4*)(cw + 3 * NUP + ca);
;         const f32x4 g = *(const f32x4*)(cw + cg_) * pg + *(const f32x4*)(cw + NUP + cg_) * ug + *(const f32x4*)(cw + 2 * NUP + cg_) * ng + *(const f32x4*)(cw + 3 * NUP + cg_);
;         float o[4];
; #pragma unroll
;         for (int j = 0; j < 4; ++j) o[j] = a[j] * g[j] / (1.0f + __expf(-g[j]));
;         u32x2 wv; wv.x = cvt_pk_bf16(o[0], o[1]); wv.y = cvt_pk_bf16(o[2], o[3]);
;         *(u32x2*)(act + (size_t)R * FFD + c) = wv;
;     }
	v_sub_u32_e32 v163, v168, v166
	v_lshrrev_b32_e32 v164, 1, v162
	v_and_b32_e32 v165, 1, v162
	v_lshrrev_b32_e32 v166, 5, v163
	v_and_b32_e32 v167, 31, v163
	v_lshlrev_b32_e32 v167, 2, v167
	v_lshl_add_u32 v166, v166, 8, v167
	v_lshlrev_b32_e32 v175, 2, v166
	v_cmp_eq_u32_e64 s[8:9], 1, v165
	v_cmp_eq_u32_e64 s[10:11], 0, v164
	s_movk_i32 s36, 0x80
	v_cmp_eq_u32_e64 s[12:13], s36, v164
	s_movk_i32 s36, 0x100
	v_cmp_eq_u32_e64 s[14:15], s36, v164
	s_or_b64 s[10:11], s[10:11], s[12:13]
	s_or_b64 s[10:11], s[10:11], s[14:15]
	v_cndmask_b32_e64 v167, 1, 0, s[10:11]
	v_or_b32_e32 v167, v167, v165
	s_movk_i32 s36, 0x7f
	v_cmp_eq_u32_e64 s[10:11], s36, v164
	s_movk_i32 s36, 0xff
	v_cmp_eq_u32_e64 s[12:13], s36, v164
	s_movk_i32 s36, 0x1ff
	v_cmp_eq_u32_e64 s[14:15], s36, v164
	s_or_b64 s[10:11], s[10:11], s[12:13]
	s_or_b64 s[10:11], s[10:11], s[14:15]
	v_cndmask_b32_e64 v168, 1, 0, s[10:11]
	v_xor_b32_e32 v166, 1, v165
	v_or_b32_e32 v168, v168, v166
	v_cvt_f32_u32_e32 v176, v167
	v_cvt_f32_u32_e32 v177, v168
	v_sub_u32_e32 v166, 0, v167
	v_cndmask_b32_e64 v169, v166, 2, s[8:9]
	v_mul_u32_u24_e32 v170, 3, v165
	v_add_u32_e32 v166, 3, v168
	v_cndmask_b32_e64 v171, 1, v166, s[8:9]
	v_lshlrev_b32_e32 v166, 2, v164
	v_add_u32_e32 v167, v166, v169
	v_mul_u32_u24_e32 v167, 0x5800, v167
	v_add_u32_e32 v172, v167, v175
	v_add_u32_e32 v167, v166, v170
	v_mul_u32_u24_e32 v167, 0x5800, v167
	v_add_u32_e32 v173, v167, v175
	v_add_u32_e32 v167, v166, v171
	v_mul_u32_u24_e32 v167, 0x5800, v167
	v_add_u32_e32 v174, v167, v175
	global_load_dwordx4 v[180:183], v172, s[40:41]
	global_load_dwordx4 v[184:187], v172, s[40:41] offset:512
	global_load_dwordx4 v[188:191], v173, s[40:41]
	global_load_dwordx4 v[192:195], v173, s[40:41] offset:512
	global_load_dwordx4 v[200:203], v174, s[40:41]
	global_load_dwordx4 v[204:207], v174, s[40:41] offset:512
	global_load_dwordx4 v[208:211], v175, s[92:93]
	global_load_dwordx4 v[212:215], v175, s[92:93] offset:512
	global_load_dwordx4 v[216:219], v175, s[96:97]
	global_load_dwordx4 v[220:223], v175, s[96:97] offset:512
	global_load_dwordx4 v[224:227], v175, s[20:21]
	global_load_dwordx4 v[228:231], v175, s[20:21] offset:512
	global_load_dwordx4 v[232:235], v175, s[84:85]
	global_load_dwordx4 v[236:239], v175, s[84:85] offset:512
	v_mul_u32_u24_e32 v166, 63, v165
	v_lshl_add_u32 v166, v164, 6, v166
	v_mul_u32_u24_e32 v179, 0x1600, v166
	v_lshl_add_u32 v179, v163, 3, v179
	s_waitcnt vmcnt(28)
	v_pk_mul_f32 v[48:49], v[48:49], v[16:17] op_sel_hi:[1,0]
	v_pk_mul_f32 v[50:51], v[50:51], v[16:17] op_sel_hi:[1,0]
	v_pk_mul_f32 v[52:53], v[52:53], v[16:17] op_sel_hi:[1,0]
	v_pk_mul_f32 v[54:55], v[54:55], v[16:17] op_sel_hi:[1,0]
	v_pk_mul_f32 v[64:65], v[64:65], v[16:17] op_sel:[0,1] op_sel_hi:[1,1]
	v_pk_mul_f32 v[66:67], v[66:67], v[16:17] op_sel:[0,1] op_sel_hi:[1,1]
	v_pk_mul_f32 v[68:69], v[68:69], v[16:17] op_sel:[0,1] op_sel_hi:[1,1]
	v_pk_mul_f32 v[70:71], v[70:71], v[16:17] op_sel:[0,1] op_sel_hi:[1,1]
	v_pk_mul_f32 v[20:21], v[48:49], v[20:21]
	v_pk_fma_f32 v[20:21], v[56:57], v[28:29], v[20:21]
	v_pk_fma_f32 v[20:21], v[64:65], v[40:41], v[20:21]
	v_pk_add_f32 v[20:21], v[20:21], v[72:73]
	v_pk_mul_f32 v[22:23], v[50:51], v[22:23]
	v_pk_fma_f32 v[22:23], v[58:59], v[30:31], v[22:23]
	v_pk_fma_f32 v[22:23], v[66:67], v[42:43], v[22:23]
	v_pk_add_f32 v[22:23], v[22:23], v[74:75]
	v_pk_mul_f32 v[24:25], v[52:53], v[24:25]
	v_pk_fma_f32 v[24:25], v[60:61], v[32:33], v[24:25]
	v_pk_fma_f32 v[24:25], v[68:69], v[44:45], v[24:25]
	v_pk_add_f32 v[24:25], v[24:25], v[76:77]
	v_pk_mul_f32 v[26:27], v[54:55], v[26:27]
	v_pk_fma_f32 v[26:27], v[62:63], v[34:35], v[26:27]
	v_pk_fma_f32 v[26:27], v[70:71], v[46:47], v[26:27]
	v_pk_add_f32 v[26:27], v[26:27], v[78:79]
	v_mul_f32_e32 v32, 0xbfb8aa3b, v24
	v_mul_f32_e32 v33, 0xbfb8aa3b, v25
	v_mul_f32_e32 v34, 0xbfb8aa3b, v26
	v_mul_f32_e32 v35, 0xbfb8aa3b, v27
	v_exp_f32_e32 v32, v32
	v_exp_f32_e32 v33, v33
	v_exp_f32_e32 v34, v34
	v_exp_f32_e32 v35, v35
	v_add_f32_e32 v32, 1.0, v32
	v_add_f32_e32 v33, 1.0, v33
	v_add_f32_e32 v34, 1.0, v34
	v_add_f32_e32 v35, 1.0, v35
	v_rcp_f32_e32 v32, v32
	v_rcp_f32_e32 v33, v33
	v_rcp_f32_e32 v34, v34
	v_rcp_f32_e32 v35, v35
	s_nop 0
	v_pk_mul_f32 v[24:25], v[24:25], v[32:33]
	v_pk_mul_f32 v[26:27], v[26:27], v[34:35]
	v_pk_mul_f32 v[20:21], v[20:21], v[24:25]
	v_pk_mul_f32 v[22:23], v[22:23], v[26:27]
	v_cvt_pk_bf16_f32 v28, v20, v21
	v_cvt_pk_bf16_f32 v29, v22, v23
	s_waitcnt vmcnt(14)
; __device__ __forceinline__ unsigned cvt_pk_bf16(float lo, float hi) { const f2_t v = {lo, hi}; const bf2_t b = __builtin_convertvector(v, bf2_t); return __builtin_bit_cast(unsigned, b); }
; __device__ void fix_phase(int wv, const Params& p, int li) {
;     ...
;         const f32x4 a = *(const f32x4*)(cw + ca) * pa + *(const f32x4*)(cw + NUP + ca) * ua + *(const f32x4*)(cw + 2 * NUP + ca) * na + *(const f32x4*)(cw + 3 * NUP + ca);
;         const f32x4 g = *(const f32x4*)(cw + cg_) * pg + *(const f32x4*)(cw + NUP + cg_) * ug + *(const f32x4*)(cw + 2 * NUP + cg_) * ng + *(const f32x4*)(cw + 3 * NUP + cg_);
;         float o[4];
; #pragma unroll
;         for (int j = 0; j < 4; ++j) o[j] = a[j] * g[j] / (1.0f + __expf(-g[j]));
;         u32x2 wv; wv.x = cvt_pk_bf16(o[0], o[1]); wv.y = cvt_pk_bf16(o[2], o[3]);
;         *(u32x2*)(act + (size_t)R * FFD + c) = wv;
;     }
	v_pk_mul_f32 v[128:129], v[128:129], v[96:97] op_sel_hi:[1,0]
	v_pk_mul_f32 v[130:131], v[130:131], v[96:97] op_sel_hi:[1,0]
	v_pk_mul_f32 v[132:133], v[132:133], v[96:97] op_sel_hi:[1,0]
	v_pk_mul_f32 v[134:135], v[134:135], v[96:97] op_sel_hi:[1,0]
	v_pk_mul_f32 v[144:145], v[144:145], v[96:97] op_sel:[0,1] op_sel_hi:[1,1]
	v_pk_mul_f32 v[146:147], v[146:147], v[96:97] op_sel:[0,1] op_sel_hi:[1,1]
	v_pk_mul_f32 v[148:149], v[148:149], v[96:97] op_sel:[0,1] op_sel_hi:[1,1]
	v_pk_mul_f32 v[150:151], v[150:151], v[96:97] op_sel:[0,1] op_sel_hi:[1,1]
	v_pk_mul_f32 v[100:101], v[128:129], v[100:101]
	v_pk_fma_f32 v[100:101], v[136:137], v[108:109], v[100:101]
	v_pk_fma_f32 v[100:101], v[144:145], v[120:121], v[100:101]
	v_pk_add_f32 v[100:101], v[100:101], v[152:153]
	v_pk_mul_f32 v[102:103], v[130:131], v[102:103]
	v_pk_fma_f32 v[102:103], v[138:139], v[110:111], v[102:103]
	v_pk_fma_f32 v[102:103], v[146:147], v[122:123], v[102:103]
	v_pk_add_f32 v[102:103], v[102:103], v[154:155]
	v_pk_mul_f32 v[104:105], v[132:133], v[104:105]
	v_pk_fma_f32 v[104:105], v[140:141], v[112:113], v[104:105]
	v_pk_fma_f32 v[104:105], v[148:149], v[124:125], v[104:105]
	v_pk_add_f32 v[104:105], v[104:105], v[156:157]
	v_pk_mul_f32 v[106:107], v[134:135], v[106:107]
	v_pk_fma_f32 v[106:107], v[142:143], v[114:115], v[106:107]
	v_pk_fma_f32 v[106:107], v[150:151], v[126:127], v[106:107]
	v_pk_add_f32 v[106:107], v[106:107], v[158:159]
	v_mul_f32_e32 v112, 0xbfb8aa3b, v104
	v_mul_f32_e32 v113, 0xbfb8aa3b, v105
	v_mul_f32_e32 v114, 0xbfb8aa3b, v106
	v_mul_f32_e32 v115, 0xbfb8aa3b, v107
	v_exp_f32_e32 v112, v112
	v_exp_f32_e32 v113, v113
	v_exp_f32_e32 v114, v114
	v_exp_f32_e32 v115, v115
	v_add_f32_e32 v112, 1.0, v112
	v_add_f32_e32 v113, 1.0, v113
	v_add_f32_e32 v114, 1.0, v114
	v_add_f32_e32 v115, 1.0, v115
	v_rcp_f32_e32 v112, v112
	v_rcp_f32_e32 v113, v113
	v_rcp_f32_e32 v114, v114
	v_rcp_f32_e32 v115, v115
	s_nop 0
	v_pk_mul_f32 v[104:105], v[104:105], v[112:113]
	v_pk_mul_f32 v[106:107], v[106:107], v[114:115]
	v_pk_mul_f32 v[100:101], v[100:101], v[104:105]
	v_pk_mul_f32 v[102:103], v[102:103], v[106:107]
	v_cvt_pk_bf16_f32 v108, v100, v101
	v_cvt_pk_bf16_f32 v109, v102, v103
	s_waitcnt vmcnt(0)
	v_pk_mul_f32 v[208:209], v[208:209], v[176:177] op_sel_hi:[1,0]
	v_pk_mul_f32 v[210:211], v[210:211], v[176:177] op_sel_hi:[1,0]
	v_pk_mul_f32 v[212:213], v[212:213], v[176:177] op_sel_hi:[1,0]
	v_pk_mul_f32 v[214:215], v[214:215], v[176:177] op_sel_hi:[1,0]
	v_pk_mul_f32 v[224:225], v[224:225], v[176:177] op_sel:[0,1] op_sel_hi:[1,1]
	v_pk_mul_f32 v[226:227], v[226:227], v[176:177] op_sel:[0,1] op_sel_hi:[1,1]
	v_pk_mul_f32 v[228:229], v[228:229], v[176:177] op_sel:[0,1] op_sel_hi:[1,1]
	v_pk_mul_f32 v[230:231], v[230:231], v[176:177] op_sel:[0,1] op_sel_hi:[1,1]
	v_pk_mul_f32 v[180:181], v[208:209], v[180:181]
	v_pk_fma_f32 v[180:181], v[216:217], v[188:189], v[180:181]
	v_pk_fma_f32 v[180:181], v[224:225], v[200:201], v[180:181]
	v_pk_add_f32 v[180:181], v[180:181], v[232:233]
	v_pk_mul_f32 v[182:183], v[210:211], v[182:183]
	v_pk_fma_f32 v[182:183], v[218:219], v[190:191], v[182:183]
	v_pk_fma_f32 v[182:183], v[226:227], v[202:203], v[182:183]
	v_pk_add_f32 v[182:183], v[182:183], v[234:235]
	v_pk_mul_f32 v[184:185], v[212:213], v[184:185]
	v_pk_fma_f32 v[184:185], v[220:221], v[192:193], v[184:185]
	v_pk_fma_f32 v[184:185], v[228:229], v[204:205], v[184:185]
	v_pk_add_f32 v[184:185], v[184:185], v[236:237]
	v_pk_mul_f32 v[186:187], v[214:215], v[186:187]
	v_pk_fma_f32 v[186:187], v[222:223], v[194:195], v[186:187]
	v_pk_fma_f32 v[186:187], v[230:231], v[206:207], v[186:187]
	v_pk_add_f32 v[186:187], v[186:187], v[238:239]
	v_mul_f32_e32 v192, 0xbfb8aa3b, v184
	v_mul_f32_e32 v193, 0xbfb8aa3b, v185
	v_mul_f32_e32 v194, 0xbfb8aa3b, v186
	v_mul_f32_e32 v195, 0xbfb8aa3b, v187
	v_exp_f32_e32 v192, v192
	v_exp_f32_e32 v193, v193
	v_exp_f32_e32 v194, v194
	v_exp_f32_e32 v195, v195
	v_add_f32_e32 v192, 1.0, v192
	v_add_f32_e32 v193, 1.0, v193
	v_add_f32_e32 v194, 1.0, v194
	v_add_f32_e32 v195, 1.0, v195
	v_rcp_f32_e32 v192, v192
	v_rcp_f32_e32 v193, v193
	v_rcp_f32_e32 v194, v194
	v_rcp_f32_e32 v195, v195
	s_nop 0
	v_pk_mul_f32 v[184:185], v[184:185], v[192:193]
	v_pk_mul_f32 v[186:187], v[186:187], v[194:195]
	v_pk_mul_f32 v[180:181], v[180:181], v[184:185]
	v_pk_mul_f32 v[182:183], v[182:183], v[186:187]
	v_cvt_pk_bf16_f32 v188, v180, v181
	v_cvt_pk_bf16_f32 v189, v182, v183
	s_mov_b64 s[6:7], exec
	v_cmp_gt_i32_e32 vcc, 0xb0000, v18
	s_and_b64 exec, s[6:7], vcc
	global_store_dwordx2 v19, v[28:29], s[76:77]
	v_cmp_gt_i32_e32 vcc, 0xb0000, v98
	s_and_b64 exec, s[6:7], vcc
	global_store_dwordx2 v99, v[108:109], s[76:77]
	v_cmp_gt_i32_e32 vcc, 0xb0000, v178
	s_and_b64 exec, s[6:7], vcc
	global_store_dwordx2 v179, v[188:189], s[76:77]
	s_mov_b64 exec, s[6:7]
	s_mul_i32 s36, s44, 3
	v_add_u32_e32 v240, s36, v240
	v_cmp_gt_i32_e32 vcc, 0xb0000, v240
	s_and_b64 exec, exec, vcc
	s_cbranch_execnz .Lfix_loop
